# attention K-loop: one static s_setprio 1 for waves 4-7 (younger half) for the duration of the loop
# speedup vs baseline: 1.0017x; 1.0001x over previous
; DI void attn_task(const Params& P, int set, int b, int kvh, int qt, char* smem) {
;     ...
; #pragma unroll
;   for (int qi = 0; qi < 2; ++qi) {
;     const float ltot = l_run[qi] + __shfl_xor(l_run[qi], 32);
;     const float inv = 1.f / ltot;
;     const size_t row = row0 + 32 * qi;
; #pragma unroll
;     for (int db = 0; db < 2; ++db)
; #pragma unroll
;       for (int g = 0; g < 4; ++g) {
;         const size_t off = row * 512 + head * 64 + db * 32 + 8 * g + 4 * hh;
;         const half4 z = *(const half4*)(zs + off);
;         const f32x16& oo = o[qi][db];
;         *(half4*)(yc + row * LDY + head * 64 + db * 32 + 8 * g + 4 * hh) = cvt4(oo[4 * g] * inv * (float)z[0], oo[4 * g + 1] * inv * (float)z[1], oo[4 * g + 2] * inv * (float)z[2], oo[4 * g + 3] * inv * (float)z[3]);
;       }
;   }
.LBB0_69:
	s_setprio 0
	v_readlane_b32 s2, v253, 31
	v_lshlrev_b32_e32 v128, 1, v174
	v_readlane_b32 s3, v253, 32
	v_lshlrev_b32_e32 v68, 3, v180
	v_mov_b32_e32 v69, v129
	v_lshl_add_u64 v[64:65], s[2:3], 0, v[128:129]
	v_readlane_b32 s2, v253, 33
	v_readlane_b32 s3, v253, 34
	v_lshl_add_u64 v[66:67], v[64:65], 0, v[68:69]
	v_mov_b32_e32 v216, v218
	v_lshl_add_u64 v[64:65], s[2:3], 0, v[128:129]
	v_lshl_add_u64 v[64:65], v[64:65], 0, v[68:69]
	ds_bpermute_b32 v68, v175, v169
	v_mad_u64_u32 v[64:65], s[2:3], v170, s4, v[64:65]
	v_mad_i32_i24 v65, v171, s4, v65
	s_waitcnt lgkmcnt(0)
	v_add_f32_e32 v68, v169, v68
	v_div_scale_f32 v69, s[2:3], v68, v68, 1.0
	v_rcp_f32_e32 v70, v69
	s_nop 0
	v_fma_f32 v71, -v69, v70, 1.0
	v_fmac_f32_e32 v70, v71, v70
	v_div_scale_f32 v71, vcc, 1.0, v68, 1.0
	v_mul_f32_e32 v72, v71, v70
	v_fma_f32 v73, -v69, v72, v71
	v_fmac_f32_e32 v72, v73, v70
	v_fma_f32 v69, -v69, v72, v71
	v_div_fmas_f32 v69, v69, v70, v72
	v_lshl_add_u64 v[70:71], v[66:67], 0, v[172:173]
	global_load_dwordx2 v[134:135], v[70:71], off
	global_load_dwordx2 v[136:137], v[70:71], off offset:16
	global_load_dwordx2 v[138:139], v[70:71], off offset:32
	global_load_dwordx2 v[140:141], v[70:71], off offset:48
	global_load_dwordx2 v[142:143], v[70:71], off offset:64
	global_load_dwordx2 v[144:145], v[70:71], off offset:80
	global_load_dwordx2 v[146:147], v[70:71], off offset:96
	global_load_dwordx2 v[148:149], v[70:71], off offset:112
	v_lshl_add_u64 v[132:133], v[66:67], 0, v[166:167]
	global_load_dwordx2 v[150:151], v[132:133], off
	global_load_dwordx2 v[152:153], v[132:133], off offset:16
	global_load_dwordx2 v[154:155], v[132:133], off offset:32
	global_load_dwordx2 v[156:157], v[132:133], off offset:48
	global_load_dwordx2 v[158:159], v[132:133], off offset:64
	global_load_dwordx2 v[160:161], v[132:133], off offset:80
	global_load_dwordx2 v[162:163], v[132:133], off offset:96
	global_load_dwordx2 v[164:165], v[132:133], off offset:112
	v_div_fixup_f32 v68, v69, v68, 1.0
	v_pk_mul_f32 v[48:49], v[48:49], v[68:69] op_sel_hi:[1,0]
	v_pk_mul_f32 v[50:51], v[50:51], v[68:69] op_sel_hi:[1,0]
	v_pk_mul_f32 v[32:33], v[32:33], v[68:69] op_sel_hi:[1,0]
	v_pk_mul_f32 v[34:35], v[34:35], v[68:69] op_sel_hi:[1,0]
	s_waitcnt vmcnt(0)
; DI void attn_task(const Params& P, int set, int b, int kvh, int qt, char* smem) {
;     ...
; #pragma unroll
;   for (int qi = 0; qi < 2; ++qi) {
;     const float ltot = l_run[qi] + __shfl_xor(l_run[qi], 32);
;     const float inv = 1.f / ltot;
;     const size_t row = row0 + 32 * qi;
; #pragma unroll
;     for (int db = 0; db < 2; ++db)
; #pragma unroll
;       for (int g = 0; g < 4; ++g) {
;         const size_t off = row * 512 + head * 64 + db * 32 + 8 * g + 4 * hh;
;         const half4 z = *(const half4*)(zs + off);
;         const f32x16& oo = o[qi][db];
;         *(half4*)(yc + row * LDY + head * 64 + db * 32 + 8 * g + 4 * hh) = cvt4(oo[4 * g] * inv * (float)z[0], oo[4 * g + 1] * inv * (float)z[1], oo[4 * g + 2] * inv * (float)z[2], oo[4 * g + 3] * inv * (float)z[3]);
;       }
;   }
	v_mov_b32_e32 v72, v134
	v_mov_b32_e32 v73, v135
	v_cvt_f32_f16_e32 v74, v72
	v_cvt_f32_f16_sdwa v75, v72 dst_sel:DWORD dst_unused:UNUSED_PAD src0_sel:WORD_1
	v_cvt_f32_f16_e32 v72, v73
	v_cvt_f32_f16_sdwa v73, v73 dst_sel:DWORD dst_unused:UNUSED_PAD src0_sel:WORD_1
	v_pk_mul_f32 v[48:49], v[48:49], v[74:75]
	s_nop 0
	v_cvt_pk_f16_f32 v48, v48, v49
	v_pk_mul_f32 v[50:51], v[50:51], v[72:73]
	s_nop 0
	v_cvt_pk_f16_f32 v49, v50, v51
	global_store_dwordx2 v[64:65], v[48:49], off
	v_mov_b32_e32 v48, v136
	v_mov_b32_e32 v49, v137
	v_pk_mul_f32 v[50:51], v[52:53], v[68:69] op_sel_hi:[1,0]
	v_cvt_f32_f16_e32 v52, v48
	v_cvt_f32_f16_sdwa v53, v48 dst_sel:DWORD dst_unused:UNUSED_PAD src0_sel:WORD_1
	v_pk_mul_f32 v[50:51], v[50:51], v[52:53]
	v_cvt_f32_f16_e32 v52, v49
	v_cvt_f32_f16_sdwa v53, v49 dst_sel:DWORD dst_unused:UNUSED_PAD src0_sel:WORD_1
	v_cvt_pk_f16_f32 v48, v50, v51
	v_pk_mul_f32 v[50:51], v[54:55], v[68:69] op_sel_hi:[1,0]
	s_nop 0
	v_pk_mul_f32 v[50:51], v[50:51], v[52:53]
	s_nop 0
	v_cvt_pk_f16_f32 v49, v50, v51
	global_store_dwordx2 v[64:65], v[48:49], off offset:16
	v_mov_b32_e32 v48, v138
	v_mov_b32_e32 v49, v139
	v_pk_mul_f32 v[50:51], v[56:57], v[68:69] op_sel_hi:[1,0]
	v_cvt_f32_f16_e32 v52, v48
	v_cvt_f32_f16_sdwa v53, v48 dst_sel:DWORD dst_unused:UNUSED_PAD src0_sel:WORD_1
	v_pk_mul_f32 v[50:51], v[50:51], v[52:53]
	v_cvt_f32_f16_e32 v52, v49
	v_cvt_f32_f16_sdwa v53, v49 dst_sel:DWORD dst_unused:UNUSED_PAD src0_sel:WORD_1
	v_cvt_pk_f16_f32 v48, v50, v51
	v_pk_mul_f32 v[50:51], v[58:59], v[68:69] op_sel_hi:[1,0]
	s_nop 0
	v_pk_mul_f32 v[50:51], v[50:51], v[52:53]
	s_nop 0
	v_cvt_pk_f16_f32 v49, v50, v51
	global_store_dwordx2 v[64:65], v[48:49], off offset:32
	v_mov_b32_e32 v48, v140
	v_mov_b32_e32 v49, v141
	v_pk_mul_f32 v[50:51], v[60:61], v[68:69] op_sel_hi:[1,0]
	v_cvt_f32_f16_e32 v52, v48
	v_cvt_f32_f16_sdwa v53, v48 dst_sel:DWORD dst_unused:UNUSED_PAD src0_sel:WORD_1
	v_pk_mul_f32 v[50:51], v[50:51], v[52:53]
	v_cvt_f32_f16_e32 v52, v49
	v_cvt_f32_f16_sdwa v53, v49 dst_sel:DWORD dst_unused:UNUSED_PAD src0_sel:WORD_1
	v_cvt_pk_f16_f32 v48, v50, v51
	v_pk_mul_f32 v[50:51], v[62:63], v[68:69] op_sel_hi:[1,0]
	s_nop 0
	v_pk_mul_f32 v[50:51], v[50:51], v[52:53]
	s_nop 0
	v_cvt_pk_f16_f32 v49, v50, v51
	global_store_dwordx2 v[64:65], v[48:49], off offset:48
	v_mov_b32_e32 v48, v142
	v_mov_b32_e32 v49, v143
	v_cvt_f32_f16_e32 v50, v48
	v_cvt_f32_f16_sdwa v51, v48 dst_sel:DWORD dst_unused:UNUSED_PAD src0_sel:WORD_1
	v_cvt_f32_f16_e32 v48, v49
	v_cvt_f32_f16_sdwa v49, v49 dst_sel:DWORD dst_unused:UNUSED_PAD src0_sel:WORD_1
	v_pk_mul_f32 v[32:33], v[32:33], v[50:51]
	s_nop 0
	v_cvt_pk_f16_f32 v32, v32, v33
	v_pk_mul_f32 v[34:35], v[34:35], v[48:49]
	s_nop 0
	v_cvt_pk_f16_f32 v33, v34, v35
	global_store_dwordx2 v[64:65], v[32:33], off offset:64
	v_mov_b32_e32 v32, v144
	v_mov_b32_e32 v33, v145
	v_pk_mul_f32 v[34:35], v[36:37], v[68:69] op_sel_hi:[1,0]
	v_cvt_f32_f16_e32 v36, v32
	v_cvt_f32_f16_sdwa v37, v32 dst_sel:DWORD dst_unused:UNUSED_PAD src0_sel:WORD_1
	v_pk_mul_f32 v[34:35], v[34:35], v[36:37]
	v_cvt_f32_f16_e32 v36, v33
	v_cvt_f32_f16_sdwa v37, v33 dst_sel:DWORD dst_unused:UNUSED_PAD src0_sel:WORD_1
	v_cvt_pk_f16_f32 v32, v34, v35
	v_pk_mul_f32 v[34:35], v[38:39], v[68:69] op_sel_hi:[1,0]
	s_nop 0
	v_pk_mul_f32 v[34:35], v[34:35], v[36:37]
	s_nop 0
	v_cvt_pk_f16_f32 v33, v34, v35
	global_store_dwordx2 v[64:65], v[32:33], off offset:80
	v_mov_b32_e32 v32, v146
	v_mov_b32_e32 v33, v147
	v_pk_mul_f32 v[34:35], v[40:41], v[68:69] op_sel_hi:[1,0]
	v_cvt_f32_f16_e32 v36, v32
	v_cvt_f32_f16_sdwa v37, v32 dst_sel:DWORD dst_unused:UNUSED_PAD src0_sel:WORD_1
	v_pk_mul_f32 v[34:35], v[34:35], v[36:37]
	v_cvt_f32_f16_e32 v36, v33
	v_cvt_f32_f16_sdwa v37, v33 dst_sel:DWORD dst_unused:UNUSED_PAD src0_sel:WORD_1
	v_cvt_pk_f16_f32 v32, v34, v35
	v_pk_mul_f32 v[34:35], v[42:43], v[68:69] op_sel_hi:[1,0]
	s_nop 0
	v_pk_mul_f32 v[34:35], v[34:35], v[36:37]
	s_nop 0
	v_cvt_pk_f16_f32 v33, v34, v35
	global_store_dwordx2 v[64:65], v[32:33], off offset:96
	v_mov_b32_e32 v32, v148
	v_mov_b32_e32 v33, v149
	v_pk_mul_f32 v[34:35], v[44:45], v[68:69] op_sel_hi:[1,0]
	v_cvt_f32_f16_e32 v36, v32
	v_cvt_f32_f16_sdwa v37, v32 dst_sel:DWORD dst_unused:UNUSED_PAD src0_sel:WORD_1
	v_pk_mul_f32 v[34:35], v[34:35], v[36:37]
	v_cvt_f32_f16_e32 v36, v33
	v_cvt_f32_f16_sdwa v37, v33 dst_sel:DWORD dst_unused:UNUSED_PAD src0_sel:WORD_1
	v_cvt_pk_f16_f32 v32, v34, v35
	v_pk_mul_f32 v[34:35], v[46:47], v[68:69] op_sel_hi:[1,0]
	s_nop 0
	v_pk_mul_f32 v[34:35], v[34:35], v[36:37]
	s_nop 0
	v_cvt_pk_f16_f32 v33, v34, v35
	global_store_dwordx2 v[64:65], v[32:33], off offset:112
	ds_bpermute_b32 v32, v175, v168
	s_waitcnt lgkmcnt(0)
	v_add_f32_e32 v32, v168, v32
	v_div_scale_f32 v33, s[2:3], v32, v32, 1.0
	v_rcp_f32_e32 v34, v33
	s_mov_b64 s[2:3], 0x9000
	v_fma_f32 v35, -v33, v34, 1.0
	v_fmac_f32_e32 v34, v35, v34
	v_div_scale_f32 v35, vcc, 1.0, v32, 1.0
	v_mul_f32_e32 v36, v35, v34
	v_fma_f32 v37, -v33, v36, v35
	v_fmac_f32_e32 v36, v37, v34
	v_fma_f32 v33, -v33, v36, v35
	v_div_fmas_f32 v33, v33, v34, v36
	v_lshl_add_u64 v[34:35], v[66:67], 0, v[166:167]
	v_mov_b32_e32 v38, v150
	v_mov_b32_e32 v39, v151
	v_div_fixup_f32 v32, v33, v32, 1.0
	v_pk_mul_f32 v[16:17], v[16:17], v[32:33] op_sel_hi:[1,0]
	v_pk_mul_f32 v[18:19], v[18:19], v[32:33] op_sel_hi:[1,0]
	v_lshl_add_u64 v[36:37], v[64:65], 0, s[2:3]
	v_cvt_f32_f16_e32 v40, v38
	v_cvt_f32_f16_sdwa v41, v38 dst_sel:DWORD dst_unused:UNUSED_PAD src0_sel:WORD_1
	v_cvt_f32_f16_e32 v38, v39
	v_cvt_f32_f16_sdwa v39, v39 dst_sel:DWORD dst_unused:UNUSED_PAD src0_sel:WORD_1
	v_pk_mul_f32 v[16:17], v[16:17], v[40:41]
	s_nop 0
	v_cvt_pk_f16_f32 v16, v16, v17
	v_pk_mul_f32 v[18:19], v[18:19], v[38:39]
	s_nop 0
	v_cvt_pk_f16_f32 v17, v18, v19
	v_add_co_u32_e32 v18, vcc, 0x9000, v64
	s_nop 1
	v_addc_co_u32_e32 v19, vcc, 0, v65, vcc
	global_store_dwordx2 v[18:19], v[16:17], off

; DI int otid() { int t = threadIdx.x; asm volatile("" : "+v"(t)); return t; }
; DI void attn_task(const Params& P, int set, int b, int kvh, int qt, char* smem) {
;   const int tid = otid(), w = tid >> 6, lane = tid & 63, r32 = lane & 31, hh = lane >> 5;
;   const int head = kvh * 4 + (w & 3), qsub = w >> 2;
;   const int nkeys = set ? CTXL : SKV;
;   const size_t row0 = (set ? (size_t)T_LAT + b * CTXL : (size_t)b * SEQ) + qt * 128 + qsub * 64 + r32;
;   const h16* qb = (const h16*)(P.ws + WS_Q);
;   h16* yc = (h16*)(P.ws + WS_YC);
;   const h16* zs = (const h16*)(P.ws + WS_ZS);
;   const h16* kg = (const h16*)(P.ws + WS_K) + (size_t)(b * 2 + kvh) * SKV * 64;
;   const h16* vg = (const h16*)(P.ws + WS_VT) + (size_t)(b * 2 + kvh) * 64 * SKV;
;   half8 qf[2][4];
; #pragma unroll
;   for (int qi = 0; qi < 2; ++qi)
; #pragma unroll
;     for (int ds = 0; ds < 4; ++ds) qf[qi][ds] = *(const half8*)(qb + (row0 + 32 * qi) * 512 + head * 64 + 16 * ds + 8 * hh);
;   const int srow = tid >> 3, sch = tid & 7, ssw = (srow >> 1) & 7;
;   const int k_wr = srow * 128 + ((sch ^ ssw) * 16);
;   const int u = sch >> 1, od = sch & 1;
;   const int v_wr0 = 8192 + srow * 128 + (((2 * u) ^ ssw) * 16) + 8 * od;
;   const int v_wr1 = 8192 + srow * 128 + (((2 * u + 1) ^ ssw) * 16) + 8 * od;
;   const int sw = (r32 >> 1) & 7;
;   const int ntile = nkeys >> 6;
;   half8 kreg = *(const half8*)(kg + (size_t)srow * 64 + sch * 8);
;   half8 vreg = *(const half8*)(vg + (size_t)srow * SKV + sch * 8);
;   {
;     char* s = smem;
;     *(half8*)(s + k_wr) = kreg;
;     half4 lo, hi;
;     lo[0] = vreg[0]; lo[1] = vreg[1]; lo[2] = vreg[2]; lo[3] = vreg[3];
;     hi[0] = vreg[4]; hi[1] = vreg[5]; hi[2] = vreg[6]; hi[3] = vreg[7];
;     *(half4*)(s + v_wr0) = lo;
;     *(half4*)(s + v_wr1) = hi;
;   }
;   __syncthreads();
;   f32x16 o[2][2];
; #pragma unroll
;   for (int qi = 0; qi < 2; ++qi)
; #pragma unroll
;     for (int v = 0; v < 16; ++v) { o[qi][0][v] = 0.f; o[qi][1][v] = 0.f; }
;   float m_run[2] = {-1e30f, -1e30f}, l_run[2] = {0.f, 0.f};
;   const float cscale = 0.125f * 1.4426950408889634f;
;   asm volatile("" : "+v"(qf[0][0]), "+v"(qf[0][1]), "+v"(qf[0][2]), "+v"(qf[0][3]), "+v"(qf[1][0]), "+v"(qf[1][1]), "+v"(qf[1][2]), "+v"(qf[1][3]));
.LBB0_82:
	s_and_b64 vcc, exec, s[2:3]
	s_cbranch_vccz .LBB0_70
	s_ashr_i32 s2, s42, 4
	s_lshl_b32 s3, s42, 1
	s_and_b32 s2, s2, -16
	s_and_b32 s3, s3, 14
	v_mov_b32_e32 v12, v208
	s_or_b32 s24, s2, s3
	s_bfe_u32 s25, s42, 0x10007
	s_ashr_i32 s2, s24, 1
	v_and_b32_e32 v0, 0xc0, v12
	v_lshl_or_b32 v174, s25, 8, v0
	v_ashrrev_i32_e32 v0, 2, v12
	s_ashr_i32 s3, s2, 31
	s_lshl_b32 s33, s42, 4
	v_and_b32_e32 v0, 0xffffffc0, v0
	v_and_b32_e32 v13, 31, v12
	s_lshl_b64 s[2:3], s[2:3], 11
	s_and_b32 s33, s33, 0x780
	v_ashrrev_i32_e32 v1, 31, v0
	v_or_b32_e32 v128, s33, v13
	v_lshl_add_u64 v[0:1], s[2:3], 0, v[0:1]
	v_readlane_b32 s2, v253, 25
	v_lshl_add_u64 v[170:171], v[0:1], 0, v[128:129]
	s_or_b32 s33, s24, s25
	v_lshlrev_b32_e32 v128, 1, v174
	v_readlane_b32 s3, v253, 26
	s_mul_i32 s24, s33, 0x48000
	s_mul_hi_i32 s25, s33, 0x48000
	v_lshl_add_u64 v[0:1], s[2:3], 0, v[128:129]
	v_readlane_b32 s2, v253, 29
	v_readlane_b32 s3, v253, 30
	s_add_u32 s2, s2, s24
	s_addc_u32 s3, s3, s25
	v_readlane_b32 s38, v253, 27
	v_ashrrev_i32_e32 v4, 3, v12
	v_bfe_u32 v180, v12, 5, 1
	v_readlane_b32 s39, v253, 28
	s_add_u32 s24, s38, s24
	v_ashrrev_i32_e32 v5, 31, v4
	v_lshlrev_b32_e32 v128, 4, v180
	s_addc_u32 s25, s39, s25
	v_and_b32_e32 v10, 7, v12
	v_lshlrev_b64 v[6:7], 7, v[4:5]
	v_lshl_add_u64 v[0:1], v[0:1], 0, v[128:129]
	v_lshlrev_b64 v[172:173], 10, v[170:171]
	v_lshl_add_u64 v[8:9], s[2:3], 0, v[6:7]
	v_lshlrev_b32_e32 v128, 4, v10
	v_mov_b64_e32 v[10:11], s[24:25]
	v_or_b32_e32 v166, 0x8000, v172
	v_mov_b32_e32 v167, v173
	v_lshl_add_u64 v[8:9], v[8:9], 0, v[128:129]
	v_mad_i64_i32 v[10:11], s[2:3], v4, s14, v[10:11]
	v_lshl_add_u64 v[2:3], v[0:1], 0, v[172:173]
	v_lshl_add_u64 v[0:1], v[0:1], 0, v[166:167]
	v_lshl_add_u64 v[10:11], v[10:11], 0, v[128:129]
	global_load_dwordx4 v[124:127], v[8:9], off
	global_load_dwordx4 v[130:133], v[10:11], off
	global_load_dwordx4 v[134:137], v[0:1], off offset:96
	global_load_dwordx4 v[138:141], v[0:1], off offset:64
	global_load_dwordx4 v[142:145], v[0:1], off offset:32
	global_load_dwordx4 v[146:149], v[0:1], off
	global_load_dwordx4 v[150:153], v[2:3], off offset:96
	global_load_dwordx4 v[154:157], v[2:3], off offset:64
	global_load_dwordx4 v[158:161], v[2:3], off offset:32
	global_load_dwordx4 v[162:165], v[2:3], off
	v_and_b32_e32 v1, 64, v214
	v_xor_b32_e32 v0, 32, v214
	v_add_u32_e32 v1, 64, v1
	v_bfe_u32 v5, v12, 4, 3
	v_and_b32_e32 v8, 6, v12
	v_lshrrev_b32_e32 v2, 5, v12
	v_lshrrev_b32_e32 v3, 4, v12
	v_lshlrev_b32_e32 v9, 3, v12
	v_bfe_u32 v10, v12, 1, 3
	v_cmp_lt_i32_e32 vcc, v0, v1
	v_bitop3_b32 v5, v8, v5, 1 bitop3:0x36
	v_lshlrev_b32_e32 v14, 7, v4
	v_cndmask_b32_e32 v11, v214, v0, vcc
	v_bitop3_b32 v12, v3, v12, 7 bitop3:0x28
	v_bitop3_b32 v3, v3, v8, 7 bitop3:0x6c
	v_and_b32_e32 v9, 8, v9
	v_mad_i64_i32 v[0:1], s[2:3], v4, s14, 0
	v_lshlrev_b32_e32 v4, 4, v5
	v_bitop3_b32 v2, v2, v10, 1 bitop3:0x6c
	v_lshl_or_b32 v181, v12, 4, v14
	v_lshlrev_b32_e32 v3, 4, v3
	v_or3_b32 v183, v4, v14, v9
	v_lshlrev_b32_e32 v184, 4, v2
	v_bitop3_b32 v2, v180, v10, 2 bitop3:0x36
	v_add_u32_e32 v5, 0, v181
	v_or3_b32 v182, v3, v14, v9
	v_add_u32_e32 v4, 0, v183
	v_lshlrev_b32_e32 v185, 4, v2
	v_bitop3_b32 v2, v180, v10, 4 bitop3:0x36
	v_add_u32_e32 v3, 0, v182
	s_waitcnt vmcnt(0)
	ds_write_b128 v5, v[124:127]
	s_waitcnt vmcnt(8)
	ds_write_b64 v3, v[130:131] offset:8192
	ds_write_b64 v4, v[132:133] offset:8192
	v_lshlrev_b32_e32 v186, 4, v2
	v_bitop3_b32 v2, v180, v10, 6 bitop3:0x36
	v_mov_b32_e32 v4, 0x48000
	v_lshlrev_b32_e32 v187, 4, v2
	v_mad_i64_i32 v[2:3], s[2:3], s33, v4, v[6:7]
	v_readlane_b32 s2, v254, 35
	v_or_b32_e32 v2, v2, v128
	v_readlane_b32 s3, v254, 36
	v_mov_b32_e32 v218, 0xbab64f3b
	v_mov_b32_e32 v215, 0x3c0881c4
	v_lshl_add_u64 v[176:177], s[2:3], 0, v[2:3]
	v_mad_i64_i32 v[0:1], s[2:3], s33, v4, v[0:1]
	v_readlane_b32 s2, v254, 37
	v_or_b32_e32 v0, v0, v128
	v_readlane_b32 s3, v254, 38
	s_mov_b32 s44, 0
	v_lshlrev_b32_e32 v175, 2, v11
	v_lshl_add_u64 v[178:179], s[2:3], 0, v[0:1]
	v_mov_b32_e32 v0, 0
	v_lshl_add_u32 v188, v13, 7, 0
	v_mov_b32_e32 v224, 0xf149f2ca
	v_mov_b32_e32 v80, 0xf149f2ca
	s_mov_b32 s43, 0
	v_mov_b32_e32 v1, v0
	v_mov_b32_e32 v2, v0
	v_mov_b32_e32 v3, v0
	v_mov_b32_e32 v4, v0
	v_mov_b32_e32 v5, v0
	v_mov_b32_e32 v6, v0
	v_mov_b32_e32 v7, v0
	v_mov_b32_e32 v8, v0
	v_mov_b32_e32 v9, v0
	v_mov_b32_e32 v10, v0
	v_mov_b32_e32 v11, v0
	v_mov_b32_e32 v12, v0
	v_mov_b32_e32 v13, v0
	v_mov_b32_e32 v14, v0
	v_mov_b32_e32 v15, v0
	v_mov_b32_e32 v16, v0
	v_mov_b32_e32 v17, v0
	v_mov_b32_e32 v18, v0
	v_mov_b32_e32 v19, v0
	v_mov_b32_e32 v20, v0
	v_mov_b32_e32 v21, v0
	v_mov_b32_e32 v22, v0
	v_mov_b32_e32 v23, v0
	v_mov_b32_e32 v24, v0
	v_mov_b32_e32 v25, v0
	v_mov_b32_e32 v26, v0
	v_mov_b32_e32 v27, v0
	v_mov_b32_e32 v28, v0
	v_mov_b32_e32 v29, v0
	v_mov_b32_e32 v30, v0
	v_mov_b32_e32 v31, v0
	v_mov_b32_e32 v32, v0
	v_mov_b32_e32 v33, v0
	v_mov_b32_e32 v34, v0
	v_mov_b32_e32 v35, v0
	v_mov_b32_e32 v36, v0
	v_mov_b32_e32 v37, v0
	v_mov_b32_e32 v38, v0
	v_mov_b32_e32 v39, v0
	v_mov_b32_e32 v40, v0
	v_mov_b32_e32 v41, v0
	v_mov_b32_e32 v42, v0
	v_mov_b32_e32 v43, v0
	v_mov_b32_e32 v44, v0
	v_mov_b32_e32 v45, v0
	v_mov_b32_e32 v46, v0
	v_mov_b32_e32 v47, v0
	v_mov_b32_e32 v48, v0
	v_mov_b32_e32 v49, v0
	v_mov_b32_e32 v50, v0
	v_mov_b32_e32 v51, v0
	v_mov_b32_e32 v52, v0
	v_mov_b32_e32 v53, v0
	v_mov_b32_e32 v54, v0
	v_mov_b32_e32 v55, v0
	v_mov_b32_e32 v56, v0
	v_mov_b32_e32 v57, v0
	v_mov_b32_e32 v58, v0
	v_mov_b32_e32 v59, v0
	v_mov_b32_e32 v60, v0
	v_mov_b32_e32 v61, v0
	v_mov_b32_e32 v62, v0
	v_mov_b32_e32 v63, v0
	v_mov_b32_e32 v168, v0
	v_mov_b32_e32 v169, v0
	s_waitcnt lgkmcnt(0)
	s_barrier
	s_waitcnt vmcnt(0)
	v_readfirstlane_b32 s2, v208
	s_nop 0
	s_lshr_b32 s2, s2, 8
	s_cmp_lg_u32 s2, 0
	s_cbranch_scc0 .Lattn_prio_skip
	s_setprio 1
; DI void attn_task(const Params& P, int set, int b, int kvh, int qt, char* smem) {
;     ...
;       float ps = 0.f;
; #pragma unroll
;       for (int v = 0; v < 16; ++v) {
;         sc[qi][0][v] = __builtin_amdgcn_exp2f(sc[qi][0][v] * cscale - m_new); ps += sc[qi][0][v];
;         sc[qi][1][v] = __builtin_amdgcn_exp2f(sc[qi][1][v] * cscale - m_new); ps += sc[qi][1][v];
;       }
;       l_run[qi] = l_run[qi] * alpha + ps;
; #pragma unroll
;       for (int v = 0; v < 16; ++v) { o[qi][0][v] *= alpha; o[qi][1][v] *= alpha; }
;     }
; #pragma unroll
;     for (int uu = 0; uu < 4; ++uu) {
;       const int co = ((2 * uu + hh) ^ sw) * 16;
;       const half8 v0 = *(const half8*)(s + 8192 + r32 * 128 + co);
;       const half8 v1 = *(const half8*)(s + 8192 + (32 + r32) * 128 + co);
; #pragma unroll
;       for (int qi = 0; qi < 2; ++qi) {
;         half8 pf;
; #pragma unroll
;         for (int j = 0; j < 8; ++j) pf[j] = (h16)((uu < 2) ? sc[qi][0][8 * (uu & 1) + j] : sc[qi][1][8 * (uu & 1) + j]);
;         o[qi][0] = __builtin_amdgcn_mfma_f32_32x32x16_f16(v0, pf, o[qi][0], 0, 0, 0);
;         o[qi][1] = __builtin_amdgcn_mfma_f32_32x32x16_f16(v1, pf, o[qi][1], 0, 0, 0);
;       }
;     }
;     if (kt + 1 < ntile) {
;       char* s2 = smem + ((kt + 1) & 1) * 16384;
;       *(half8*)(s2 + k_wr) = kreg;
;       half4 lo, hi;
;       lo[0] = vreg[0]; lo[1] = vreg[1]; lo[2] = vreg[2]; lo[3] = vreg[3];
;       hi[0] = vreg[4]; hi[1] = vreg[5]; hi[2] = vreg[6]; hi[3] = vreg[7];
;       *(half4*)(s2 + v_wr0) = lo;
;       *(half4*)(s2 + v_wr1) = hi;
;     }
;     __syncthreads();
;   }
.Lattn_prio_skip:
	s_branch .LBB0_85
.LBB0_84:
	v_add_f32_e32 v91, 0, v189
	v_add_f32_e32 v92, 0, v119
	v_add_f32_e32 v91, v190, v91
	v_add_f32_e32 v80, v80, v92
	v_add_f32_e32 v91, v191, v91
	v_add_f32_e32 v80, v120, v80
	v_add_f32_e32 v91, v192, v91
	v_add_f32_e32 v80, v87, v80
	v_add_f32_e32 v91, v193, v91
	v_add_f32_e32 v80, v121, v80
	v_add_f32_e32 v91, v194, v91
	v_add_f32_e32 v80, v81, v80
	v_add_f32_e32 v91, v195, v91
	v_add_f32_e32 v80, v122, v80
	v_add_f32_e32 v91, v196, v91
	v_add_f32_e32 v80, v86, v80
	v_add_f32_e32 v91, v197, v91
	v_add_f32_e32 v80, v100, v80
	v_add_f32_e32 v91, v198, v91
	v_add_f32_e32 v80, v84, v80
	v_add_f32_e32 v91, v199, v91
	v_add_f32_e32 v80, v101, v80
	v_add_f32_e32 v91, v200, v91
	v_add_f32_e32 v80, v85, v80
	v_add_f32_e32 v91, v201, v91
	v_add_f32_e32 v80, v102, v80
	v_add_f32_e32 v91, v202, v91
	v_add_f32_e32 v80, v82, v80
	v_add_f32_e32 v91, v203, v91
	v_add_f32_e32 v80, v103, v80
	v_add_f32_e32 v91, v204, v91
	v_add_f32_e32 v80, v83, v80
	v_add_f32_e32 v91, v116, v91
	v_add_f32_e32 v80, v104, v80
	v_add_f32_e32 v91, v205, v91
	v_add_f32_e32 v80, v88, v80
	v_add_f32_e32 v91, v117, v91
	v_add_f32_e32 v80, v106, v80
	v_add_f32_e32 v91, v206, v91
	v_add_f32_e32 v80, v90, v80
	v_add_f32_e32 v91, v118, v91
	v_add_f32_e32 v80, v105, v80
	v_add_f32_e32 v91, v207, v91
	v_add_f32_e32 v90, v89, v80
	v_pk_add_f32 v[80:81], v[112:113], v[90:91]
	v_mov_b32_e32 v97, v114
	v_pk_add_f32 v[72:73], v[72:73], v[80:81]
	s_add_i32 s43, s43, 1
	v_pk_add_f32 v[70:71], v[70:71], v[72:73]
	s_mov_b64 s[2:3], 0x2000
	v_pk_add_f32 v[68:69], v[68:69], v[70:71]
	v_lshl_add_u64 v[176:177], v[176:177], 0, s[2:3]
	v_pk_add_f32 v[66:67], v[66:67], v[68:69]
	v_lshl_add_u64 v[178:179], v[178:179], 0, s[22:23]
	v_pk_add_f32 v[64:65], v[64:65], v[66:67]
	s_cmp_lg_u32 s43, 36
	v_pk_add_f32 v[64:65], v[76:77], v[64:65]
	s_mov_b32 s44, s24
	v_pk_add_f32 v[64:65], v[98:99], v[64:65]
	v_mov_b32_e32 v224, v115
	v_pk_add_f32 v[64:65], v[74:75], v[64:65]
	v_mov_b32_e32 v80, v128
	v_pk_add_f32 v[64:65], v[78:79], v[64:65]
	s_waitcnt lgkmcnt(0)
	v_pk_fma_f32 v[168:169], v[168:169], v[96:97], v[64:65]
	s_barrier
	s_cbranch_scc0 .LBB0_69
